# v95 plus one static s_setprio 1 for waves 4-7 across the P5 work-queue phase (NSA / mLSTM, two waves per SIMD sharing the VALU), reset to 0 before the P5->P6 sync
# baseline (speedup 1.0000x reference)
.LBB0_316:
	s_or_b64 exec, exec, s[4:5]
	v_readfirstlane_b32 s0, v254
	s_nop 3
	s_lshr_b32 s0, s0, 6
	s_cmp_ge_u32 s0, 4
	s_cbranch_scc0 .Lp5prio_done
	s_setprio 1
.Lp5prio_done:
	s_mov_b32 s101, 0
	s_add_u32 s1, s68, 0x162e0800
	s_addc_u32 s26, s69, 0
	s_add_u32 s46, s68, 0x1d00800
	v_mov_b32_e32 v183, v254
	s_addc_u32 s47, s69, 0
	v_mbcnt_lo_u32_b32 v0, -1, 0
	s_barrier
	s_add_u32 s27, s68, 0x1f2e0800
	v_and_b32_e32 v182, 63, v183
	v_mbcnt_hi_u32_b32 v181, -1, v0
	v_bfrev_b32_e32 v0, 0.5
	v_readfirstlane_b32 s0, v183
	s_mov_b32 s13, 0
	v_cmp_eq_u32_e64 s[4:5], 0, v182
	s_addc_u32 s52, s69, 0
	v_mov_b32_e32 v157, 0
	s_mov_b32 s53, 0x1e2e0000
	s_mov_b32 s54, 0x1e2e1000
	s_mov_b32 s55, 0x1e2e2000
	s_mov_b32 s70, 0x2280000
	s_mov_b32 s71, 0x2281000
	s_mov_b32 s72, 0x2282000
	s_mov_b32 s73, 0x2283000
	s_mov_b32 s74, 0x2284000
	s_mov_b32 s75, 0x5040100
	s_mov_b64 s[14:15], 0x100
	s_mov_b64 s[16:17], 0x4000
	s_mov_b64 s[18:19], 0x2000
	v_and_b32_e32 v184, 64, v181
	v_lshl_or_b32 v185, v181, 2, v0
	v_mov_b32_e32 v186, 0x3f803f80
	v_mov_b32_e32 v187, 0x80
	s_lshr_b32 s98, s0, 6
	s_cmp_eq_u32 s98, 0
	s_cbranch_scc1 .LBB0_319
	s_cmp_lg_u32 s98, 2
	s_cbranch_scc1 .LBB0_366
	s_cmp_gt_u32 s2, 31
	s_cbranch_scc1 .LBB0_366
	s_branch .LBB0_319

.LBB0_463:
	s_setprio 0
	s_waitcnt vmcnt(0) lgkmcnt(0)
	s_barrier
	s_and_saveexec_b64 s[4:5], s[72:73]
	s_cbranch_execz .LBB0_473
	buffer_wbl2 sc1
	s_load_dwordx2 s[8:9], s[70:71], -0x8
	s_mul_i32 s10, s33, 4
	v_mov_b32_e32 v2, 0
	v_mov_b32_e32 v3, 1
	s_waitcnt vmcnt(0) lgkmcnt(0)
	global_atomic_add v1, v2, v3, s[8:9] offset:2048 sc0
	s_waitcnt vmcnt(0)
	v_readfirstlane_b32 s11, v1
	s_add_i32 s11, s11, 1
	s_cmp_lg_u32 s11, s10
	s_cbranch_scc1 .Lgb3_poll
	global_atomic_add v2, v3, s[8:9] offset:3072
